# code placement: attention tile-loop heads and GEMM K-loop heads aligned to 64 bytes
# baseline (speedup 1.0000x reference)
.Latt_swa_p0:
	.p2align	6

.LBB0_223:
	s_ashr_i32 s29, s28, 31
	s_lshl_b64 s[20:21], s[28:29], 19
	s_add_u32 s34, s50, s20
	s_addc_u32 s35, s51, s21
	s_and_b64 s[20:21], s[6:7], exec
	s_cselect_b32 s9, s35, s39
	s_cselect_b32 s11, s34, s38
	s_ashr_i32 s27, s26, 31
	s_lshl_b64 s[20:21], s[26:27], 19
	s_add_u32 s36, s1, s20
	s_addc_u32 s37, s4, s21
	s_and_b64 s[20:21], s[6:7], exec
	s_cselect_b32 s20, s37, s45
	s_cselect_b32 s21, s36, s44
	s_add_u32 s27, s44, 0x100
	s_addc_u32 s29, s45, 0
	s_mov_b32 s73, -2
	.p2align	6

.LBB0_272:
	s_ashr_i32 s27, s26, 31
	s_lshl_b64 s[30:31], s[26:27], 19
	s_add_u32 s36, s0, s30
	s_addc_u32 s37, s1, s31
	s_and_b64 s[30:31], s[6:7], exec
	s_cselect_b32 s27, s37, s29
	s_cselect_b32 s53, s36, s28
	s_ashr_i32 s25, s24, 31
	s_lshl_b64 s[30:31], s[24:25], 19
	s_add_u32 s38, s50, s30
	s_addc_u32 s39, s51, s31
	s_and_b64 s[30:31], s[6:7], exec
	s_cselect_b32 s25, s39, s35
	s_cselect_b32 s55, s38, s34
	s_add_u32 s56, s34, 0x100
	s_addc_u32 s57, s35, 0
	s_add_u32 s28, s28, 0x40080
	s_addc_u32 s29, s29, 0
	s_mov_b32 s58, -2
	.p2align	6

.LBB0_295:
	s_add_u32 s52, s34, 0x100
	s_addc_u32 s53, s35, 0
	s_mov_b32 s55, -2
	.p2align	6

.LBB0_343:
	s_ashr_i32 s19, s18, 31
	s_lshl_b64 s[26:27], s[18:19], 17
	s_add_u32 s26, s0, s26
	s_addc_u32 s27, s1, s27
	s_and_b64 s[28:29], s[6:7], exec
	s_cselect_b32 s19, s27, s35
	s_cselect_b32 s57, s26, s34
	s_ashr_i32 s17, s16, 31
	s_lshl_b64 s[28:29], s[16:17], 17
	s_add_u32 s28, s4, s28
	s_addc_u32 s29, s5, s29
	s_and_b64 s[30:31], s[6:7], exec
	s_cselect_b32 s17, s29, s37
	s_cselect_b32 s58, s28, s36
	s_mov_b32 s46, 0
	s_mov_b64 s[38:39], -1
	s_mov_b64 s[44:45], 0
	.p2align	6

.LBB0_359:
	s_ashr_i32 s15, s14, 31
	s_lshl_b64 s[26:27], s[14:15], 17
	s_add_u32 s26, s4, s26
	s_addc_u32 s27, s5, s27
	s_and_b64 s[28:29], s[6:7], exec
	s_cselect_b32 s15, s27, s19
	s_cselect_b32 s55, s26, s18
	s_ashr_i32 s13, s12, 31
	s_lshl_b64 s[28:29], s[12:13], 17
	s_add_u32 s28, s0, s28
	s_addc_u32 s29, s1, s29
	s_and_b64 s[30:31], s[6:7], exec
	s_cselect_b32 s13, s29, s25
	s_cselect_b32 s56, s28, s24
	s_mov_b32 s38, 0
	s_mov_b64 s[34:35], -1
	s_mov_b64 s[36:37], 0
	.p2align	6

.LBB0_394:
	s_ashr_i32 s21, s20, 31
	s_lshl_b64 s[22:23], s[20:21], 19
	s_add_u32 s22, s4, s22
	s_addc_u32 s23, s5, s23
	s_and_b64 s[24:25], s[6:7], exec
	s_cselect_b32 s21, s23, s15
	s_cselect_b32 s44, s22, s14
	s_ashr_i32 s19, s18, 31
	s_lshl_b64 s[24:25], s[18:19], 19
	s_add_u32 s24, s28, s24
	s_addc_u32 s25, s29, s25
	s_and_b64 s[26:27], s[6:7], exec
	s_cselect_b32 s19, s25, s17
	s_cselect_b32 s45, s24, s16
	s_add_u32 s46, s16, 0x100
	s_addc_u32 s47, s17, 0
	s_add_u32 s14, s14, 0x40080
	s_addc_u32 s15, s15, 0
	s_mov_b32 s48, -2
	.p2align	6

.LBB0_450:
	s_add_i32 s21, s5, -2
	s_add_u32 s45, s50, 0x100
	s_addc_u32 vcc_lo, s51, 0
	s_add_u32 s8, s60, 0x80
	s_addc_u32 s9, s61, 0
	s_mov_b32 s50, 0
	.p2align	6

.LBB0_637:
	s_ashr_i32 s15, s14, 31
	s_lshl_b64 s[16:17], s[14:15], 19
	s_add_u32 s16, s37, s16
	s_addc_u32 s17, s38, s17
	s_and_b64 s[18:19], s[6:7], exec
	s_cselect_b32 s15, s17, s25
	s_cselect_b32 s21, s16, s24
	s_ashr_i32 s13, s12, 31
	s_lshl_b64 s[18:19], s[12:13], 19
	s_add_u32 s18, s39, s18
	s_addc_u32 s19, s44, s19
	s_and_b64 s[28:29], s[6:7], exec
	s_cselect_b32 s13, s19, s27
	s_cselect_b32 s23, s18, s26
	s_add_u32 s49, s26, 0x100
	s_addc_u32 s50, s27, 0
	s_add_u32 s24, s24, 0x40080
	s_addc_u32 s25, s25, 0
	s_mov_b32 s51, -2
	.p2align	6
